# P0 LoRA weight image: the five gathered elements per thread loaded together instead of five dependent round trips (plus hand-written P0 transposes)
# speedup vs baseline: 1.0097x; 1.0021x over previous
.Lp0tr_done:
.LBB0_346:
	s_waitcnt vmcnt(0)
	v_readlane_b32 s4, v241, 12
	v_readlane_b32 s5, v241, 13
	v_readlane_b32 s6, v241, 16
	v_readlane_b32 s7, v241, 17
	v_readlane_b32 s8, v241, 18
	v_readlane_b32 s9, v241, 19
	s_add_u32 s10, s30, 0x27b0000
	s_addc_u32 s11, s31, 0
	v_lshl_add_u32 v64, s2, 9, v182
	v_mov_b32_e32 v116, s4
	v_mov_b32_e32 v117, s5
	v_mov_b32_e32 v118, s6
	v_mov_b32_e32 v119, s7
	v_mov_b32_e32 v120, s8
	v_mov_b32_e32 v121, s9
	v_mov_b32_e32 v68, v64
	v_lshrrev_b32_e32 v66, 9, v68
	v_mul_u32_u24_e32 v66, 0xcccd, v66
	v_lshrrev_b32_e32 v66, 18, v66
	v_mul_u32_u24_e32 v67, 0xa00, v66
	v_sub_u32_e32 v67, v68, v67
	v_lshl_add_u32 v74, v67, 8, v66
	v_lshlrev_b32_e32 v74, 1, v74
	v_lshrrev_b32_e32 v68, 10, v67
	v_lshlrev_b32_e32 v69, 6, v68
	v_sub_u32_e32 v69, v66, v69
	v_lshrrev_b32_e32 v75, 1, v68
	v_lshlrev_b32_e64 v75, v75, 64
	v_cmp_lt_u32_e64 s[12:13], v69, v75
	v_bfe_u32 v72, v67, 9, 1
	v_lshlrev_b32_e32 v72, 6, v72
	v_cmp_gt_u32_e64 s[14:15], 2, v68
	s_nop 1
	v_cndmask_b32_e64 v72, 0, v72, s[14:15]
	v_add_u32_e32 v72, v72, v69
	v_and_b32_e32 v75, 0x1ff, v67
	v_lshl_add_u32 v72, v72, 9, v75
	v_lshlrev_b32_e32 v72, 2, v72
	v_cndmask_b32_e64 v72, 0, v72, s[12:13]
	v_cmp_eq_u32_e64 s[16:17], 1, v68
	v_cmp_eq_u32_e64 s[18:19], 2, v68
	s_nop 1
	s_and_b64 s[16:17], s[16:17], s[12:13]
	s_and_b64 s[18:19], s[18:19], s[12:13]
	v_cndmask_b32_e64 v70, v116, v118, s[16:17]
	v_cndmask_b32_e64 v71, v117, v119, s[16:17]
	v_cndmask_b32_e64 v70, v70, v120, s[18:19]
	v_cndmask_b32_e64 v71, v71, v121, s[18:19]
	v_mov_b32_e32 v75, 0
	v_add_co_u32_e32 v70, vcc, v70, v72
	s_nop 1
	v_addc_co_u32_e32 v71, vcc, 0, v71, vcc
	v_cndmask_b32_e64 v75, 0, 1.0, s[12:13]
	global_load_dword v73, v[70:71], off
	v_add_u32_e32 v78, 0x20000, v64
	v_lshrrev_b32_e32 v76, 9, v78
	v_mul_u32_u24_e32 v76, 0xcccd, v76
	v_lshrrev_b32_e32 v76, 18, v76
	v_mul_u32_u24_e32 v77, 0xa00, v76
	v_sub_u32_e32 v77, v78, v77
	v_lshl_add_u32 v84, v77, 8, v76
	v_lshlrev_b32_e32 v84, 1, v84
	v_lshrrev_b32_e32 v78, 10, v77
	v_lshlrev_b32_e32 v79, 6, v78
	v_sub_u32_e32 v79, v76, v79
	v_lshrrev_b32_e32 v85, 1, v78
	v_lshlrev_b32_e64 v85, v85, 64
	v_cmp_lt_u32_e64 s[12:13], v79, v85
	v_bfe_u32 v82, v77, 9, 1
	v_lshlrev_b32_e32 v82, 6, v82
	v_cmp_gt_u32_e64 s[14:15], 2, v78
	s_nop 1
	v_cndmask_b32_e64 v82, 0, v82, s[14:15]
	v_add_u32_e32 v82, v82, v79
	v_and_b32_e32 v85, 0x1ff, v77
	v_lshl_add_u32 v82, v82, 9, v85
	v_lshlrev_b32_e32 v82, 2, v82
	v_cndmask_b32_e64 v82, 0, v82, s[12:13]
	v_cmp_eq_u32_e64 s[16:17], 1, v78
	v_cmp_eq_u32_e64 s[18:19], 2, v78
	s_nop 1
	s_and_b64 s[16:17], s[16:17], s[12:13]
	s_and_b64 s[18:19], s[18:19], s[12:13]
	v_cndmask_b32_e64 v80, v116, v118, s[16:17]
	v_cndmask_b32_e64 v81, v117, v119, s[16:17]
	v_cndmask_b32_e64 v80, v80, v120, s[18:19]
	v_cndmask_b32_e64 v81, v81, v121, s[18:19]
	v_mov_b32_e32 v85, 0
	v_add_co_u32_e32 v80, vcc, v80, v82
	s_nop 1
	v_addc_co_u32_e32 v81, vcc, 0, v81, vcc
	v_cndmask_b32_e64 v85, 0, 1.0, s[12:13]
	global_load_dword v83, v[80:81], off
	v_add_u32_e32 v88, 0x40000, v64
	v_lshrrev_b32_e32 v86, 9, v88
	v_mul_u32_u24_e32 v86, 0xcccd, v86
	v_lshrrev_b32_e32 v86, 18, v86
	v_mul_u32_u24_e32 v87, 0xa00, v86
	v_sub_u32_e32 v87, v88, v87
	v_lshl_add_u32 v94, v87, 8, v86
	v_lshlrev_b32_e32 v94, 1, v94
	v_lshrrev_b32_e32 v88, 10, v87
	v_lshlrev_b32_e32 v89, 6, v88
	v_sub_u32_e32 v89, v86, v89
	v_lshrrev_b32_e32 v95, 1, v88
	v_lshlrev_b32_e64 v95, v95, 64
	v_cmp_lt_u32_e64 s[12:13], v89, v95
	v_bfe_u32 v92, v87, 9, 1
	v_lshlrev_b32_e32 v92, 6, v92
	v_cmp_gt_u32_e64 s[14:15], 2, v88
	s_nop 1
	v_cndmask_b32_e64 v92, 0, v92, s[14:15]
	v_add_u32_e32 v92, v92, v89
	v_and_b32_e32 v95, 0x1ff, v87
	v_lshl_add_u32 v92, v92, 9, v95
	v_lshlrev_b32_e32 v92, 2, v92
	v_cndmask_b32_e64 v92, 0, v92, s[12:13]
	v_cmp_eq_u32_e64 s[16:17], 1, v88
	v_cmp_eq_u32_e64 s[18:19], 2, v88
	s_nop 1
	s_and_b64 s[16:17], s[16:17], s[12:13]
	s_and_b64 s[18:19], s[18:19], s[12:13]
	v_cndmask_b32_e64 v90, v116, v118, s[16:17]
	v_cndmask_b32_e64 v91, v117, v119, s[16:17]
	v_cndmask_b32_e64 v90, v90, v120, s[18:19]
	v_cndmask_b32_e64 v91, v91, v121, s[18:19]
	v_mov_b32_e32 v95, 0
	v_add_co_u32_e32 v90, vcc, v90, v92
	s_nop 1
	v_addc_co_u32_e32 v91, vcc, 0, v91, vcc
	v_cndmask_b32_e64 v95, 0, 1.0, s[12:13]
	global_load_dword v93, v[90:91], off
	v_add_u32_e32 v98, 0x60000, v64
	v_lshrrev_b32_e32 v96, 9, v98
	v_mul_u32_u24_e32 v96, 0xcccd, v96
	v_lshrrev_b32_e32 v96, 18, v96
	v_mul_u32_u24_e32 v97, 0xa00, v96
	v_sub_u32_e32 v97, v98, v97
	v_lshl_add_u32 v104, v97, 8, v96
	v_lshlrev_b32_e32 v104, 1, v104
	v_lshrrev_b32_e32 v98, 10, v97
	v_lshlrev_b32_e32 v99, 6, v98
	v_sub_u32_e32 v99, v96, v99
	v_lshrrev_b32_e32 v105, 1, v98
	v_lshlrev_b32_e64 v105, v105, 64
	v_cmp_lt_u32_e64 s[12:13], v99, v105
	v_bfe_u32 v102, v97, 9, 1
	v_lshlrev_b32_e32 v102, 6, v102
	v_cmp_gt_u32_e64 s[14:15], 2, v98
	s_nop 1
	v_cndmask_b32_e64 v102, 0, v102, s[14:15]
	v_add_u32_e32 v102, v102, v99
	v_and_b32_e32 v105, 0x1ff, v97
	v_lshl_add_u32 v102, v102, 9, v105
	v_lshlrev_b32_e32 v102, 2, v102
	v_cndmask_b32_e64 v102, 0, v102, s[12:13]
	v_cmp_eq_u32_e64 s[16:17], 1, v98
	v_cmp_eq_u32_e64 s[18:19], 2, v98
	s_nop 1
	s_and_b64 s[16:17], s[16:17], s[12:13]
	s_and_b64 s[18:19], s[18:19], s[12:13]
	v_cndmask_b32_e64 v100, v116, v118, s[16:17]
	v_cndmask_b32_e64 v101, v117, v119, s[16:17]
	v_cndmask_b32_e64 v100, v100, v120, s[18:19]
	v_cndmask_b32_e64 v101, v101, v121, s[18:19]
	v_mov_b32_e32 v105, 0
	v_add_co_u32_e32 v100, vcc, v100, v102
	s_nop 1
	v_addc_co_u32_e32 v101, vcc, 0, v101, vcc
	v_cndmask_b32_e64 v105, 0, 1.0, s[12:13]
	global_load_dword v103, v[100:101], off
	v_add_u32_e32 v108, 0x80000, v64
	v_lshrrev_b32_e32 v106, 9, v108
	v_mul_u32_u24_e32 v106, 0xcccd, v106
	v_lshrrev_b32_e32 v106, 18, v106
	v_mul_u32_u24_e32 v107, 0xa00, v106
	v_sub_u32_e32 v107, v108, v107
	v_lshl_add_u32 v114, v107, 8, v106
	v_lshlrev_b32_e32 v114, 1, v114
	v_lshrrev_b32_e32 v108, 10, v107
	v_lshlrev_b32_e32 v109, 6, v108
	v_sub_u32_e32 v109, v106, v109
	v_lshrrev_b32_e32 v115, 1, v108
	v_lshlrev_b32_e64 v115, v115, 64
	v_cmp_lt_u32_e64 s[12:13], v109, v115
	v_bfe_u32 v112, v107, 9, 1
	v_lshlrev_b32_e32 v112, 6, v112
	v_cmp_gt_u32_e64 s[14:15], 2, v108
	s_nop 1
	v_cndmask_b32_e64 v112, 0, v112, s[14:15]
	v_add_u32_e32 v112, v112, v109
	v_and_b32_e32 v115, 0x1ff, v107
	v_lshl_add_u32 v112, v112, 9, v115
	v_lshlrev_b32_e32 v112, 2, v112
	v_cndmask_b32_e64 v112, 0, v112, s[12:13]
	v_cmp_eq_u32_e64 s[16:17], 1, v108
	v_cmp_eq_u32_e64 s[18:19], 2, v108
	s_nop 1
	s_and_b64 s[16:17], s[16:17], s[12:13]
	s_and_b64 s[18:19], s[18:19], s[12:13]
	v_cndmask_b32_e64 v110, v116, v118, s[16:17]
	v_cndmask_b32_e64 v111, v117, v119, s[16:17]
	v_cndmask_b32_e64 v110, v110, v120, s[18:19]
	v_cndmask_b32_e64 v111, v111, v121, s[18:19]
	v_mov_b32_e32 v115, 0
	v_add_co_u32_e32 v110, vcc, v110, v112
	s_nop 1
	v_addc_co_u32_e32 v111, vcc, 0, v111, vcc
	v_cndmask_b32_e64 v115, 0, 1.0, s[12:13]
	global_load_dword v113, v[110:111], off
	s_waitcnt vmcnt(4)
	v_cmp_ne_u32_e32 vcc, 0, v75
	s_nop 1
	v_cndmask_b32_e32 v73, 0, v73, vcc
	v_cvt_pk_bf16_f32 v73, v73, v73
	global_store_short v74, v73, s[10:11]
	s_waitcnt vmcnt(3)
	v_cmp_ne_u32_e32 vcc, 0, v85
	s_nop 1
	v_cndmask_b32_e32 v83, 0, v83, vcc
	v_cvt_pk_bf16_f32 v83, v83, v83
	global_store_short v84, v83, s[10:11]
	s_waitcnt vmcnt(2)
	v_cmp_ne_u32_e32 vcc, 0, v95
	s_nop 1
	v_cndmask_b32_e32 v93, 0, v93, vcc
	v_cvt_pk_bf16_f32 v93, v93, v93
	global_store_short v94, v93, s[10:11]
	s_waitcnt vmcnt(1)
	v_cmp_ne_u32_e32 vcc, 0, v105
	s_nop 1
	v_cndmask_b32_e32 v103, 0, v103, vcc
	v_cvt_pk_bf16_f32 v103, v103, v103
	global_store_short v104, v103, s[10:11]
	s_waitcnt vmcnt(0)
	v_cmp_ne_u32_e32 vcc, 0, v115
	s_nop 1
	v_cndmask_b32_e32 v113, 0, v113, vcc
	v_cvt_pk_bf16_f32 v113, v113, v113
	global_store_short v114, v113, s[10:11]
	v_readlane_b32 s4, v241, 16
	v_readlane_b32 s5, v241, 17
	v_readlane_b32 s6, v241, 18
	v_readlane_b32 s7, v241, 19
	v_readlane_b32 s8, v241, 20
	v_readlane_b32 s9, v241, 21
	v_readlane_b32 s10, v241, 22
	v_readlane_b32 s11, v241, 23
	v_readlane_b32 s12, v241, 24
	v_readlane_b32 s13, v241, 25
	v_readlane_b32 s14, v241, 26
	v_readlane_b32 s15, v241, 27
	v_readlane_b32 s16, v241, 28
	v_readlane_b32 s17, v241, 29
	v_readlane_b32 s18, v241, 30
	v_readlane_b32 s19, v241, 31
	s_mov_b64 s[0:1], exec
